# chunk-state propagation chain on the f32 matrix cores (v_mfma_f32_16x16x4_f32): transposed state kept in accumulator registers and reused as B operand, P staged f32 in LDS
# speedup vs baseline: 1.0401x; 1.0046x over previous
; #define LAS __attribute__((address_space(3)))
; DI unsigned pack2(float lo, float hi) { f32x2 v = {lo, hi}; bf16v2 r = __builtin_convertvector(v, bf16v2); return __builtin_bit_cast(unsigned, r); }
; DI float lo_bf(unsigned u) { return __uint_as_float(u << 16); }
; DI float hi_bf(unsigned u) { return __uint_as_float(u & 0xffff0000u); }
; DI void propagate_chain(int wv, const Params& p, int chain, LAS unsigned char* lds) {
;     unsigned char* ob = (unsigned char*)p.out;
;     bf16_t* UU = (bf16_t*)(ob + O_U); const bf16_t* PT = (const bf16_t*)(ob + O_PT);
;     const int seq = chain >> 3, hd = (chain >> 1) & 3, dir = chain & 1;
;     const int nch = seq == 0 ? NCP : NCS, gbase = seq == 0 ? 0 : NCP + (seq - 1) * NCS;
;     const int tid = tid_(wv), i = tid >> 3, jb = tid & 7;
;     LAS float* Ssm = (LAS float*)lds;
;     LAS float* Psm = (LAS float*)(lds + 17408);
;     float S[8];
; #pragma unroll
;     for (int e = 0; e < 8; ++e) S[e] = 0.f;
;     u32x4 u4, p4;
;     { const int c = dir == 0 ? 0 : nch - 1; const size_t item = ((size_t)(gbase + c) * 4 + hd) * 2 + dir;
;       u4 = *(const u32x4*)(UU + (item * 64 + i) * 64 + 8 * jb); p4 = *(const u32x4*)(PT + (item * 64 + i) * 64 + 8 * jb); }
;     for (int step = 0; step < nch; ++step) {
;         const int c = dir == 0 ? step : nch - 1 - step; const size_t item = ((size_t)(gbase + c) * 4 + hd) * 2 + dir;
;         bf16_t* up = UU + (item * 64 + i) * 64 + 8 * jb;
;         __syncthreads();
; #pragma unroll
;         for (int e = 0; e < 4; ++e) { Psm[i * 64 + 8 * jb + 2 * e] = lo_bf(p4[e]); Psm[i * 64 + 8 * jb + 2 * e + 1] = hi_bf(p4[e]); }
; #pragma unroll
;         for (int e = 0; e < 8; ++e) Ssm[i * 68 + 8 * jb + e] = S[e];
;         { u32x4 so = {pack2(S[0], S[1]), pack2(S[2], S[3]), pack2(S[4], S[5]), pack2(S[6], S[7])}; *(u32x4*)up = so; }
;         __syncthreads();
;         float acc[8];
; #pragma unroll
;         for (int e = 0; e < 4; ++e) { acc[2 * e] = lo_bf(u4[e]); acc[2 * e + 1] = hi_bf(u4[e]); }
;         if (step + 1 < nch) {
;             const int c2 = dir == 0 ? step + 1 : nch - 2 - step; const size_t item2 = ((size_t)(gbase + c2) * 4 + hd) * 2 + dir;
;             u4 = *(const u32x4*)(UU + (item2 * 64 + i) * 64 + 8 * jb); p4 = *(const u32x4*)(PT + (item2 * 64 + i) * 64 + 8 * jb);
;         }
.LBB0_1238:
	s_andn2_b64 vcc, exec, s[6:7]
	s_cbranch_vccnz .LBB0_981
	v_writelane_b32 v255, s4, 17
	v_writelane_b32 v255, s5, 18
	v_writelane_b32 v255, s6, 19
	v_writelane_b32 v255, s7, 20
	v_writelane_b32 v255, s8, 21
	v_writelane_b32 v255, s9, 22
	v_writelane_b32 v255, s10, 23
	v_writelane_b32 v255, s11, 24
	v_writelane_b32 v255, s12, 25
	v_writelane_b32 v255, s13, 26
	v_writelane_b32 v255, s14, 27
	v_writelane_b32 v255, s15, 28
	v_writelane_b32 v255, s16, 29
	v_writelane_b32 v255, s17, 30
	v_writelane_b32 v255, s18, 31
	v_writelane_b32 v255, s19, 32
	v_writelane_b32 v255, s20, 33
	v_writelane_b32 v255, s21, 34
	v_writelane_b32 v255, s22, 35
	v_writelane_b32 v255, s23, 36
	v_writelane_b32 v255, s24, 37
	v_writelane_b32 v255, s25, 38
	v_writelane_b32 v255, s26, 39
	v_writelane_b32 v255, s27, 40
	v_writelane_b32 v255, s28, 41
	v_writelane_b32 v255, s29, 42
	v_writelane_b32 v255, s30, 43
	v_writelane_b32 v255, s31, 44
	v_writelane_b32 v255, s36, 45
	v_writelane_b32 v255, s37, 46
	v_writelane_b32 v255, s38, 47
	v_writelane_b32 v255, s39, 48
	v_writelane_b32 v255, s40, 49
	v_writelane_b32 v255, s41, 50
	v_writelane_b32 v255, s42, 51
	v_writelane_b32 v255, s43, 52
	v_writelane_b32 v255, s44, 53
	v_writelane_b32 v255, s45, 54
	v_writelane_b32 v255, s46, 55
	v_writelane_b32 v255, s47, 56
	v_writelane_b32 v255, s48, 57
	v_writelane_b32 v255, s49, 58
	v_writelane_b32 v255, s50, 59
	v_writelane_b32 v255, s51, 60
	s_load_dwordx2 s[40:41], s[0:1], 0x120
	s_lshr_b32 s10, s61, 3
	s_bfe_u32 s9, s61, 0x20001
	s_and_b32 s8, s61, 1
	s_mul_i32 s4, s10, 17
	s_add_u32 s4, s4, 0x70
	s_cmp_eq_u32 s10, 0
	s_cselect_b32 s4, 0, s4
	s_cselect_b32 s11, 0x81, 17
	s_sub_u32 s5, s11, 1
	s_mov_b32 s20, 0xffff0000
	s_cmp_eq_u32 s8, 0
	s_cselect_b32 s5, 0, s5
	s_cselect_b32 s20, 0x10000, s20
	s_cselect_b32 s21, 0, -1
	s_add_u32 s4, s4, s5
	s_lshl_b32 s4, s4, 2
	s_add_u32 s4, s4, s9
	s_lshl_b32 s4, s4, 1
	s_add_u32 s4, s4, s8
	s_lshl_b32 s4, s4, 13
	s_lshr_b32 s14, s33, 6
	s_waitcnt lgkmcnt(0)
	s_add_u32 s16, s40, 0xb5b0000
	s_addc_u32 s17, s41, 0
	s_add_u32 s16, s16, s4
	s_addc_u32 s17, s17, 0
	s_add_u32 s18, s40, 0xdfc0000
	s_addc_u32 s19, s41, 0
	s_add_u32 s18, s18, s4
	s_addc_u32 s19, s19, 0
	v_add_u32_e32 v2, s33, v254
	v_lshrrev_b32_e32 v3, 3, v2
	v_and_b32_e32 v8, 7, v2
	v_mul_u32_u24_e32 v3, 0x110, v3
	v_lshl_add_u32 v3, v8, 5, v3
	v_lshlrev_b32_e32 v2, 4, v2
	v_and_b32_e32 v8, 15, v254
	v_lshrrev_b32_e32 v9, 4, v254
	v_mul_u32_u24_e32 v16, 0x440, v9
	v_lshl_add_u32 v16, v8, 2, v16
	s_lshl_b32 s4, s14, 4
	v_add_u32_e32 v17, s4, v8
	v_lshlrev_b32_e32 v17, 7, v17
	v_lshl_add_u32 v17, v9, 3, v17
	v_mov_b32_e32 v20, 0
	v_mov_b32_e32 v21, 0
	v_mov_b32_e32 v22, 0
	v_mov_b32_e32 v23, 0
	v_mov_b32_e32 v24, 0
	v_mov_b32_e32 v25, 0
	v_mov_b32_e32 v26, 0
	v_mov_b32_e32 v27, 0
	v_mov_b32_e32 v28, 0
	v_mov_b32_e32 v29, 0
	v_mov_b32_e32 v30, 0
	v_mov_b32_e32 v31, 0
	v_mov_b32_e32 v32, 0
	v_mov_b32_e32 v33, 0
	v_mov_b32_e32 v34, 0
	v_mov_b32_e32 v35, 0
	global_load_dwordx4 v[4:7], v2, s[18:19]
	s_cmpk_gt_u32 s14, 3
	s_cbranch_scc1 .Lchna_pro1
	global_load_dwordx2 v[52:53], v17, s[16:17] offset:0
	global_load_dwordx2 v[54:55], v17, s[16:17] offset:32
	global_load_dwordx2 v[56:57], v17, s[16:17] offset:64
	global_load_dwordx2 v[58:59], v17, s[16:17] offset:96
.Lchna_pro1:
	s_add_u32 s18, s18, s20
	s_addc_u32 s19, s19, s21
	s_waitcnt vmcnt(0)
	s_mov_b32 s15, 0x0
	v_lshlrev_b32_e32 v8, 16, v4
	v_and_b32_e32 v9, 0xffff0000, v4
	v_lshlrev_b32_e32 v10, 16, v5
	v_and_b32_e32 v11, 0xffff0000, v5
	v_lshlrev_b32_e32 v12, 16, v6
	v_and_b32_e32 v13, 0xffff0000, v6
	v_lshlrev_b32_e32 v14, 16, v7
	v_and_b32_e32 v15, 0xffff0000, v7
	v_add_u32_e32 v18, s15, v3
	ds_write_b128 v18, v[8:11]
	ds_write_b128 v18, v[12:15] offset:16
	s_cmpk_lt_u32 s11, 2
	s_cbranch_scc1 .Lchna_pro2
	global_load_dwordx4 v[4:7], v2, s[18:19]
	s_add_u32 s18, s18, s20
	s_addc_u32 s19, s19, s21
.Lchna_pro2:
	s_mov_b32 s12, 0
	s_mov_b32 s15, 0x0
	s_mov_b32 s13, 0x4400
	s_waitcnt lgkmcnt(0)
	s_barrier
.Lchna_loop:
	s_add_u32 s4, s12, 1
	s_cmp_lt_u32 s4, s11
	s_cbranch_scc0 .Lchna_nostage
	s_waitcnt vmcnt(0)
	v_lshlrev_b32_e32 v8, 16, v4
	v_and_b32_e32 v9, 0xffff0000, v4
	v_lshlrev_b32_e32 v10, 16, v5
	v_and_b32_e32 v11, 0xffff0000, v5
	v_lshlrev_b32_e32 v12, 16, v6
	v_and_b32_e32 v13, 0xffff0000, v6
	v_lshlrev_b32_e32 v14, 16, v7
	v_and_b32_e32 v15, 0xffff0000, v7
	v_add_u32_e32 v18, s13, v3
	ds_write_b128 v18, v[8:11]
	ds_write_b128 v18, v[12:15] offset:16
	s_add_u32 s4, s12, 2
	s_cmp_lt_u32 s4, s11
	s_cbranch_scc0 .Lchna_nostage
	global_load_dwordx4 v[4:7], v2, s[18:19]
	s_add_u32 s18, s18, s20
	s_addc_u32 s19, s19, s21
; #define LAS __attribute__((address_space(3)))
; DI unsigned pack2(float lo, float hi) { f32x2 v = {lo, hi}; bf16v2 r = __builtin_convertvector(v, bf16v2); return __builtin_bit_cast(unsigned, r); }
; DI float lo_bf(unsigned u) { return __uint_as_float(u << 16); }
; DI float hi_bf(unsigned u) { return __uint_as_float(u & 0xffff0000u); }
; DI void propagate_chain(int wv, const Params& p, int chain, LAS unsigned char* lds) {
;     ...
;     for (int step = 0; step < nch; ++step) {
;         const int c = dir == 0 ? step : nch - 1 - step; const size_t item = ((size_t)(gbase + c) * 4 + hd) * 2 + dir;
;         bf16_t* up = UU + (item * 64 + i) * 64 + 8 * jb;
;         __syncthreads();
; #pragma unroll
;         for (int e = 0; e < 4; ++e) { Psm[i * 64 + 8 * jb + 2 * e] = lo_bf(p4[e]); Psm[i * 64 + 8 * jb + 2 * e + 1] = hi_bf(p4[e]); }
; #pragma unroll
;         for (int e = 0; e < 8; ++e) Ssm[i * 68 + 8 * jb + e] = S[e];
;         { u32x4 so = {pack2(S[0], S[1]), pack2(S[2], S[3]), pack2(S[4], S[5]), pack2(S[6], S[7])}; *(u32x4*)up = so; }
;         __syncthreads();
;         float acc[8];
; #pragma unroll
;         for (int e = 0; e < 4; ++e) { acc[2 * e] = lo_bf(u4[e]); acc[2 * e + 1] = hi_bf(u4[e]); }
;         if (step + 1 < nch) {
;             const int c2 = dir == 0 ? step + 1 : nch - 2 - step; const size_t item2 = ((size_t)(gbase + c2) * 4 + hd) * 2 + dir;
;             u4 = *(const u32x4*)(UU + (item2 * 64 + i) * 64 + 8 * jb); p4 = *(const u32x4*)(PT + (item2 * 64 + i) * 64 + 8 * jb);
;         }
; #pragma unroll 8
;         for (int k = 0; k < 64; ++k) {
;             const float sv = Ssm[i * 68 + k];
;             const f32x4 a = *(const LAS f32x4*)(Psm + k * 64 + 8 * jb), b = *(const LAS f32x4*)(Psm + k * 64 + 8 * jb + 4);
; #pragma unroll
;             for (int e = 0; e < 4; ++e) { acc[e] += sv * a[e]; acc[4 + e] += sv * b[e]; }
;         }
; #pragma unroll
;         for (int e = 0; e < 8; ++e) S[e] = acc[e];
.Lchna_nostage:
	s_cmpk_gt_u32 s14, 3
	s_cbranch_scc1 .Lchna_sync
	s_waitcnt vmcnt(0)
	v_lshlrev_b32_e32 v36, 16, v52
	v_and_b32_e32 v37, 0xffff0000, v52
	v_lshlrev_b32_e32 v38, 16, v53
	v_and_b32_e32 v39, 0xffff0000, v53
	v_lshlrev_b32_e32 v40, 16, v54
	v_and_b32_e32 v41, 0xffff0000, v54
	v_lshlrev_b32_e32 v42, 16, v55
	v_and_b32_e32 v43, 0xffff0000, v55
	v_lshlrev_b32_e32 v44, 16, v56
	v_and_b32_e32 v45, 0xffff0000, v56
	v_lshlrev_b32_e32 v46, 16, v57
	v_and_b32_e32 v47, 0xffff0000, v57
	v_lshlrev_b32_e32 v48, 16, v58
	v_and_b32_e32 v49, 0xffff0000, v58
	v_lshlrev_b32_e32 v50, 16, v59
	v_and_b32_e32 v51, 0xffff0000, v59
	v_cvt_pk_bf16_f32 v128, v20, v21
	v_cvt_pk_bf16_f32 v129, v22, v23
	v_cvt_pk_bf16_f32 v130, v24, v25
	v_cvt_pk_bf16_f32 v131, v26, v27
	v_cvt_pk_bf16_f32 v132, v28, v29
	v_cvt_pk_bf16_f32 v133, v30, v31
	v_cvt_pk_bf16_f32 v134, v32, v33
	v_cvt_pk_bf16_f32 v135, v34, v35
	global_store_dwordx2 v17, v[128:129], s[16:17] offset:0
	global_store_dwordx2 v17, v[130:131], s[16:17] offset:32
	global_store_dwordx2 v17, v[132:133], s[16:17] offset:64
	global_store_dwordx2 v17, v[134:135], s[16:17] offset:96
	s_add_u32 s16, s16, s20
	s_addc_u32 s17, s17, s21
	s_add_u32 s4, s12, 1
	s_cmp_lt_u32 s4, s11
	s_cbranch_scc0 .Lchna_sync
	global_load_dwordx2 v[52:53], v17, s[16:17] offset:0
	global_load_dwordx2 v[54:55], v17, s[16:17] offset:32
	global_load_dwordx2 v[56:57], v17, s[16:17] offset:64
	global_load_dwordx2 v[58:59], v17, s[16:17] offset:96
	v_add_u32_e32 v18, s15, v16
	ds_read_b32 v64, v18 offset:0
	ds_read_b32 v80, v18 offset:64
	ds_read_b32 v96, v18 offset:128
	ds_read_b32 v112, v18 offset:192
	ds_read_b32 v65, v18 offset:272
	ds_read_b32 v81, v18 offset:336
	ds_read_b32 v97, v18 offset:400
	ds_read_b32 v113, v18 offset:464
	ds_read_b32 v66, v18 offset:544
	ds_read_b32 v82, v18 offset:608
	ds_read_b32 v98, v18 offset:672
	ds_read_b32 v114, v18 offset:736
	ds_read_b32 v67, v18 offset:816
	ds_read_b32 v83, v18 offset:880
	ds_read_b32 v99, v18 offset:944
	ds_read_b32 v115, v18 offset:1008
	ds_read_b32 v68, v18 offset:4352
	ds_read_b32 v84, v18 offset:4416
	ds_read_b32 v100, v18 offset:4480
	ds_read_b32 v116, v18 offset:4544
	ds_read_b32 v69, v18 offset:4624
	ds_read_b32 v85, v18 offset:4688
	ds_read_b32 v101, v18 offset:4752
	ds_read_b32 v117, v18 offset:4816
	ds_read_b32 v70, v18 offset:4896
	ds_read_b32 v86, v18 offset:4960
	ds_read_b32 v102, v18 offset:5024
	ds_read_b32 v118, v18 offset:5088
	ds_read_b32 v71, v18 offset:5168
	ds_read_b32 v87, v18 offset:5232
	ds_read_b32 v103, v18 offset:5296
	ds_read_b32 v119, v18 offset:5360
	s_waitcnt lgkmcnt(15)
	v_mfma_f32_16x16x4_f32 v[36:39], v64, v20, v[36:39]
	v_mfma_f32_16x16x4_f32 v[40:43], v80, v20, v[40:43]
	v_mfma_f32_16x16x4_f32 v[44:47], v96, v20, v[44:47]
	v_mfma_f32_16x16x4_f32 v[48:51], v112, v20, v[48:51]
	v_mfma_f32_16x16x4_f32 v[36:39], v65, v21, v[36:39]
	v_mfma_f32_16x16x4_f32 v[40:43], v81, v21, v[40:43]
	v_mfma_f32_16x16x4_f32 v[44:47], v97, v21, v[44:47]
	v_mfma_f32_16x16x4_f32 v[48:51], v113, v21, v[48:51]
	v_mfma_f32_16x16x4_f32 v[36:39], v66, v22, v[36:39]
	v_mfma_f32_16x16x4_f32 v[40:43], v82, v22, v[40:43]
	v_mfma_f32_16x16x4_f32 v[44:47], v98, v22, v[44:47]
	v_mfma_f32_16x16x4_f32 v[48:51], v114, v22, v[48:51]
	v_mfma_f32_16x16x4_f32 v[36:39], v67, v23, v[36:39]
	v_mfma_f32_16x16x4_f32 v[40:43], v83, v23, v[40:43]
	v_mfma_f32_16x16x4_f32 v[44:47], v99, v23, v[44:47]
	v_mfma_f32_16x16x4_f32 v[48:51], v115, v23, v[48:51]
	ds_read_b32 v72, v18 offset:8704
	ds_read_b32 v88, v18 offset:8768
	ds_read_b32 v104, v18 offset:8832
	ds_read_b32 v120, v18 offset:8896
	ds_read_b32 v73, v18 offset:8976
	ds_read_b32 v89, v18 offset:9040
	ds_read_b32 v105, v18 offset:9104
	ds_read_b32 v121, v18 offset:9168
	ds_read_b32 v74, v18 offset:9248
	ds_read_b32 v90, v18 offset:9312
	ds_read_b32 v106, v18 offset:9376
	ds_read_b32 v122, v18 offset:9440
	ds_read_b32 v75, v18 offset:9520
	ds_read_b32 v91, v18 offset:9584
	ds_read_b32 v107, v18 offset:9648
	ds_read_b32 v123, v18 offset:9712
	s_waitcnt lgkmcnt(15)
; #define LAS __attribute__((address_space(3)))
; DI void propagate_chain(int wv, const Params& p, int chain, LAS unsigned char* lds) {
;     ...
; #pragma unroll 8
;         for (int k = 0; k < 64; ++k) {
;             const float sv = Ssm[i * 68 + k];
;             const f32x4 a = *(const LAS f32x4*)(Psm + k * 64 + 8 * jb), b = *(const LAS f32x4*)(Psm + k * 64 + 8 * jb + 4);
; #pragma unroll
;             for (int e = 0; e < 4; ++e) { acc[e] += sv * a[e]; acc[4 + e] += sv * b[e]; }
;         }
; #pragma unroll
;         for (int e = 0; e < 8; ++e) S[e] = acc[e];
;     }
;     __syncthreads();
; }
	v_mfma_f32_16x16x4_f32 v[36:39], v68, v24, v[36:39]
	v_mfma_f32_16x16x4_f32 v[40:43], v84, v24, v[40:43]
	v_mfma_f32_16x16x4_f32 v[44:47], v100, v24, v[44:47]
	v_mfma_f32_16x16x4_f32 v[48:51], v116, v24, v[48:51]
	v_mfma_f32_16x16x4_f32 v[36:39], v69, v25, v[36:39]
	v_mfma_f32_16x16x4_f32 v[40:43], v85, v25, v[40:43]
	v_mfma_f32_16x16x4_f32 v[44:47], v101, v25, v[44:47]
	v_mfma_f32_16x16x4_f32 v[48:51], v117, v25, v[48:51]
	v_mfma_f32_16x16x4_f32 v[36:39], v70, v26, v[36:39]
	v_mfma_f32_16x16x4_f32 v[40:43], v86, v26, v[40:43]
	v_mfma_f32_16x16x4_f32 v[44:47], v102, v26, v[44:47]
	v_mfma_f32_16x16x4_f32 v[48:51], v118, v26, v[48:51]
	v_mfma_f32_16x16x4_f32 v[36:39], v71, v27, v[36:39]
	v_mfma_f32_16x16x4_f32 v[40:43], v87, v27, v[40:43]
	v_mfma_f32_16x16x4_f32 v[44:47], v103, v27, v[44:47]
	v_mfma_f32_16x16x4_f32 v[48:51], v119, v27, v[48:51]
	ds_read_b32 v76, v18 offset:13056
	ds_read_b32 v92, v18 offset:13120
	ds_read_b32 v108, v18 offset:13184
	ds_read_b32 v124, v18 offset:13248
	ds_read_b32 v77, v18 offset:13328
	ds_read_b32 v93, v18 offset:13392
	ds_read_b32 v109, v18 offset:13456
	ds_read_b32 v125, v18 offset:13520
	ds_read_b32 v78, v18 offset:13600
	ds_read_b32 v94, v18 offset:13664
	ds_read_b32 v110, v18 offset:13728
	ds_read_b32 v126, v18 offset:13792
	ds_read_b32 v79, v18 offset:13872
	ds_read_b32 v95, v18 offset:13936
	ds_read_b32 v111, v18 offset:14000
	ds_read_b32 v127, v18 offset:14064
	s_waitcnt lgkmcnt(15)
	v_mfma_f32_16x16x4_f32 v[36:39], v72, v28, v[36:39]
	v_mfma_f32_16x16x4_f32 v[40:43], v88, v28, v[40:43]
	v_mfma_f32_16x16x4_f32 v[44:47], v104, v28, v[44:47]
	v_mfma_f32_16x16x4_f32 v[48:51], v120, v28, v[48:51]
	v_mfma_f32_16x16x4_f32 v[36:39], v73, v29, v[36:39]
	v_mfma_f32_16x16x4_f32 v[40:43], v89, v29, v[40:43]
	v_mfma_f32_16x16x4_f32 v[44:47], v105, v29, v[44:47]
	v_mfma_f32_16x16x4_f32 v[48:51], v121, v29, v[48:51]
	v_mfma_f32_16x16x4_f32 v[36:39], v74, v30, v[36:39]
	v_mfma_f32_16x16x4_f32 v[40:43], v90, v30, v[40:43]
	v_mfma_f32_16x16x4_f32 v[44:47], v106, v30, v[44:47]
	v_mfma_f32_16x16x4_f32 v[48:51], v122, v30, v[48:51]
	v_mfma_f32_16x16x4_f32 v[36:39], v75, v31, v[36:39]
	v_mfma_f32_16x16x4_f32 v[40:43], v91, v31, v[40:43]
	v_mfma_f32_16x16x4_f32 v[44:47], v107, v31, v[44:47]
	v_mfma_f32_16x16x4_f32 v[48:51], v123, v31, v[48:51]
	s_waitcnt lgkmcnt(0)
	v_mfma_f32_16x16x4_f32 v[36:39], v76, v32, v[36:39]
	v_mfma_f32_16x16x4_f32 v[40:43], v92, v32, v[40:43]
	v_mfma_f32_16x16x4_f32 v[44:47], v108, v32, v[44:47]
	v_mfma_f32_16x16x4_f32 v[48:51], v124, v32, v[48:51]
	v_mfma_f32_16x16x4_f32 v[36:39], v77, v33, v[36:39]
	v_mfma_f32_16x16x4_f32 v[40:43], v93, v33, v[40:43]
	v_mfma_f32_16x16x4_f32 v[44:47], v109, v33, v[44:47]
	v_mfma_f32_16x16x4_f32 v[48:51], v125, v33, v[48:51]
	v_mfma_f32_16x16x4_f32 v[36:39], v78, v34, v[36:39]
	v_mfma_f32_16x16x4_f32 v[40:43], v94, v34, v[40:43]
	v_mfma_f32_16x16x4_f32 v[44:47], v110, v34, v[44:47]
	v_mfma_f32_16x16x4_f32 v[48:51], v126, v34, v[48:51]
	v_mfma_f32_16x16x4_f32 v[36:39], v79, v35, v[36:39]
	v_mfma_f32_16x16x4_f32 v[40:43], v95, v35, v[40:43]
	v_mfma_f32_16x16x4_f32 v[44:47], v111, v35, v[44:47]
	v_mfma_f32_16x16x4_f32 v[48:51], v127, v35, v[48:51]
	s_nop 15
	v_mov_b32_e32 v20, v36
	v_mov_b32_e32 v21, v37
	v_mov_b32_e32 v22, v38
	v_mov_b32_e32 v23, v39
	v_mov_b32_e32 v24, v40
	v_mov_b32_e32 v25, v41
	v_mov_b32_e32 v26, v42
	v_mov_b32_e32 v27, v43
	v_mov_b32_e32 v28, v44
	v_mov_b32_e32 v29, v45
	v_mov_b32_e32 v30, v46
	v_mov_b32_e32 v31, v47
	v_mov_b32_e32 v32, v48
	v_mov_b32_e32 v33, v49
	v_mov_b32_e32 v34, v50
	v_mov_b32_e32 v35, v51
.Lchna_sync:
	s_mov_b32 s4, s15
	s_mov_b32 s15, s13
	s_mov_b32 s13, s4
	s_waitcnt lgkmcnt(0)
	s_barrier
	s_add_u32 s12, s12, 1
	s_cmp_lt_u32 s12, s11
	s_cbranch_scc1 .Lchna_loop
	s_waitcnt vmcnt(0)
	s_barrier
	v_readlane_b32 s4, v255, 17
	v_readlane_b32 s5, v255, 18
	v_readlane_b32 s6, v255, 19
	v_readlane_b32 s7, v255, 20
	v_readlane_b32 s8, v255, 21
	v_readlane_b32 s9, v255, 22
	v_readlane_b32 s10, v255, 23
	v_readlane_b32 s11, v255, 24
	v_readlane_b32 s12, v255, 25
	v_readlane_b32 s13, v255, 26
	v_readlane_b32 s14, v255, 27
	v_readlane_b32 s15, v255, 28
	v_readlane_b32 s16, v255, 29
	v_readlane_b32 s17, v255, 30
	v_readlane_b32 s18, v255, 31
	v_readlane_b32 s19, v255, 32
	v_readlane_b32 s20, v255, 33
	v_readlane_b32 s21, v255, 34
	v_readlane_b32 s22, v255, 35
	v_readlane_b32 s23, v255, 36
	v_readlane_b32 s24, v255, 37
	v_readlane_b32 s25, v255, 38
	v_readlane_b32 s26, v255, 39
	v_readlane_b32 s27, v255, 40
	v_readlane_b32 s28, v255, 41
	v_readlane_b32 s29, v255, 42
	v_readlane_b32 s30, v255, 43
	v_readlane_b32 s31, v255, 44
	v_readlane_b32 s36, v255, 45
	v_readlane_b32 s37, v255, 46
	v_readlane_b32 s38, v255, 47
	v_readlane_b32 s39, v255, 48
	v_readlane_b32 s40, v255, 49
	v_readlane_b32 s41, v255, 50
	v_readlane_b32 s42, v255, 51
	v_readlane_b32 s43, v255, 52
	v_readlane_b32 s44, v255, 53
	v_readlane_b32 s45, v255, 54
	v_readlane_b32 s46, v255, 55
	v_readlane_b32 s47, v255, 56
	v_readlane_b32 s48, v255, 57
	v_readlane_b32 s49, v255, 58
	v_readlane_b32 s50, v255, 59
	v_readlane_b32 s51, v255, 60
	s_nop 4
	s_branch .LBB0_981

; #define LAS __attribute__((address_space(3)))
; DI void propagate_chain(int wv, const Params& p, int chain, LAS unsigned char* lds) {
;     unsigned char* ob = (unsigned char*)p.out;
;     bf16_t* UU = (bf16_t*)(ob + O_U); const bf16_t* PT = (const bf16_t*)(ob + O_PT);
;     const int seq = chain >> 3, hd = (chain >> 1) & 3, dir = chain & 1;
;     const int nch = seq == 0 ? NCP : NCS, gbase = seq == 0 ? 0 : NCP + (seq - 1) * NCS;
;     const int tid = tid_(wv), i = tid >> 3, jb = tid & 7;
;     LAS float* Ssm = (LAS float*)lds;
;     LAS float* Psm = (LAS float*)(lds + 17408);
;     float S[8];
; #pragma unroll
;     for (int e = 0; e < 8; ++e) S[e] = 0.f;
;     u32x4 u4, p4;
;     { const int c = dir == 0 ? 0 : nch - 1; const size_t item = ((size_t)(gbase + c) * 4 + hd) * 2 + dir;
;       u4 = *(const u32x4*)(UU + (item * 64 + i) * 64 + 8 * jb); p4 = *(const u32x4*)(PT + (item * 64 + i) * 64 + 8 * jb); }
;     for (int step = 0; step < nch; ++step) {
.LBB0_2872:
	s_andn2_b64 vcc, exec, s[4:5]
	s_cbranch_vccnz .LBB0_2615
	v_writelane_b32 v255, s4, 17
	v_writelane_b32 v255, s5, 18
	v_writelane_b32 v255, s6, 19
	v_writelane_b32 v255, s7, 20
	v_writelane_b32 v255, s8, 21
	v_writelane_b32 v255, s9, 22
	v_writelane_b32 v255, s10, 23
	v_writelane_b32 v255, s11, 24
	v_writelane_b32 v255, s12, 25
	v_writelane_b32 v255, s13, 26
	v_writelane_b32 v255, s14, 27
	v_writelane_b32 v255, s15, 28
	v_writelane_b32 v255, s16, 29
	v_writelane_b32 v255, s17, 30
	v_writelane_b32 v255, s18, 31
	v_writelane_b32 v255, s19, 32
	v_writelane_b32 v255, s20, 33
	v_writelane_b32 v255, s21, 34
	v_writelane_b32 v255, s22, 35
	v_writelane_b32 v255, s23, 36
	v_writelane_b32 v255, s24, 37
	v_writelane_b32 v255, s25, 38
	v_writelane_b32 v255, s26, 39
	v_writelane_b32 v255, s27, 40
	v_writelane_b32 v255, s28, 41
	v_writelane_b32 v255, s29, 42
	v_writelane_b32 v255, s30, 43
	v_writelane_b32 v255, s31, 44
	v_writelane_b32 v255, s36, 45
	v_writelane_b32 v255, s37, 46
	v_writelane_b32 v255, s38, 47
	v_writelane_b32 v255, s39, 48
	v_writelane_b32 v255, s40, 49
	v_writelane_b32 v255, s41, 50
	v_writelane_b32 v255, s42, 51
	v_writelane_b32 v255, s43, 52
	v_writelane_b32 v255, s44, 53
	v_writelane_b32 v255, s45, 54
	v_writelane_b32 v255, s46, 55
	v_writelane_b32 v255, s47, 56
	v_writelane_b32 v255, s48, 57
	v_writelane_b32 v255, s49, 58
	v_writelane_b32 v255, s50, 59
	v_writelane_b32 v255, s51, 60
	s_load_dwordx2 s[40:41], s[0:1], 0x120
	s_lshr_b32 s10, s87, 3
	s_bfe_u32 s9, s87, 0x20001
	s_and_b32 s8, s87, 1
	s_mul_i32 s4, s10, 17
	s_add_u32 s4, s4, 0x70
	s_cmp_eq_u32 s10, 0
	s_cselect_b32 s4, 0, s4
	s_cselect_b32 s11, 0x81, 17
	s_sub_u32 s5, s11, 1
	s_mov_b32 s20, 0xffff0000
	s_cmp_eq_u32 s8, 0
	s_cselect_b32 s5, 0, s5
	s_cselect_b32 s20, 0x10000, s20
	s_cselect_b32 s21, 0, -1
	s_add_u32 s4, s4, s5
	s_lshl_b32 s4, s4, 2
	s_add_u32 s4, s4, s9
	s_lshl_b32 s4, s4, 1
	s_add_u32 s4, s4, s8
	s_lshl_b32 s4, s4, 13
	s_lshr_b32 s14, s33, 6
	s_waitcnt lgkmcnt(0)
	s_add_u32 s16, s40, 0xb5b0000
	s_addc_u32 s17, s41, 0
	s_add_u32 s16, s16, s4
	s_addc_u32 s17, s17, 0
	s_add_u32 s18, s40, 0xdfc0000
	s_addc_u32 s19, s41, 0
	s_add_u32 s18, s18, s4
	s_addc_u32 s19, s19, 0
	v_add_u32_e32 v2, s33, v254
	v_lshrrev_b32_e32 v3, 3, v2
	v_and_b32_e32 v8, 7, v2
	v_mul_u32_u24_e32 v3, 0x110, v3
	v_lshl_add_u32 v3, v8, 5, v3
	v_lshlrev_b32_e32 v2, 4, v2
	v_and_b32_e32 v8, 15, v254
	v_lshrrev_b32_e32 v9, 4, v254
	v_mul_u32_u24_e32 v16, 0x440, v9
	v_lshl_add_u32 v16, v8, 2, v16
	s_lshl_b32 s4, s14, 4
	v_add_u32_e32 v17, s4, v8
	v_lshlrev_b32_e32 v17, 7, v17
	v_lshl_add_u32 v17, v9, 3, v17
	v_mov_b32_e32 v20, 0
	v_mov_b32_e32 v21, 0
	v_mov_b32_e32 v22, 0
	v_mov_b32_e32 v23, 0
	v_mov_b32_e32 v24, 0
	v_mov_b32_e32 v25, 0
	v_mov_b32_e32 v26, 0
	v_mov_b32_e32 v27, 0
	v_mov_b32_e32 v28, 0
	v_mov_b32_e32 v29, 0
	v_mov_b32_e32 v30, 0
	v_mov_b32_e32 v31, 0
	v_mov_b32_e32 v32, 0
	v_mov_b32_e32 v33, 0
	v_mov_b32_e32 v34, 0
	v_mov_b32_e32 v35, 0
	global_load_dwordx4 v[4:7], v2, s[18:19]
	s_cmpk_gt_u32 s14, 3
	s_cbranch_scc1 .Lchnb_pro1
	global_load_dwordx2 v[52:53], v17, s[16:17] offset:0
	global_load_dwordx2 v[54:55], v17, s[16:17] offset:32
	global_load_dwordx2 v[56:57], v17, s[16:17] offset:64
	global_load_dwordx2 v[58:59], v17, s[16:17] offset:96
